# static priority raise (s_setprio 1) for the waves running the serial S5 scan in the mixer phase, reset after the scan
# baseline (speedup 1.0000x reference)
.LBB0_428:
	s_or_saveexec_b64 s[4:5], s[14:15]
	v_readlane_b32 s6, v255, 10
	v_readlane_b32 s7, v255, 11
	s_lshl_b64 s[8:9], s[6:7], 11
	s_lshl_b64 s[14:15], s[6:7], 15
	s_xor_b64 exec, exec, s[4:5]
	v_cvt_i32_f32_e32 v53, v59
	s_mov_b32 s6, 0xbfc90fda
	v_fma_f32 v54, v59, s6, |v31|
	v_fmac_f32_e32 v54, 0xb3a22168, v59
	v_fmac_f32_e32 v54, 0xa7c234c4, v59
	s_or_b64 exec, exec, s[4:5]
	v_mul_f32_e32 v57, v38, v34
	v_mul_f32_e32 v58, 0x3fb8aa3b, v57
	s_mov_b32 s17, 0x3fb8aa3b
	v_fma_f32 v59, v57, s17, -v58
	v_rndne_f32_e32 v60, v58
	v_fmac_f32_e32 v59, 0x32a5705f, v57
	v_sub_f32_e32 v58, v58, v60
	v_add_f32_e32 v58, v58, v59
	v_exp_f32_e32 v58, v58
	v_cvt_i32_f32_e32 v59, v60
	s_mov_b32 s18, 0xc2ce8ed0
	v_cmp_ngt_f32_e32 vcc, s18, v57
	s_mov_b32 s19, 0x42b17218
	v_ldexp_f32 v58, v58, v59
	v_cndmask_b32_e32 v58, 0, v58, vcc
	v_cmp_nlt_f32_e32 vcc, s19, v57
	v_mov_b32_e32 v64, 0x7f800000
	v_mov_b32_e32 v61, 0x3c0881c4
	v_cndmask_b32_e32 v57, v64, v58, vcc
	v_mul_f32_e32 v58, v56, v56
	v_fmamk_f32 v59, v58, 0xb94c1982, v61
	v_fmaak_f32 v59, v58, v59, 0xbe2aaa9d
	v_mul_f32_e32 v59, v58, v59
	v_mov_b32_e32 v62, 0xbab64f3b
	v_fmac_f32_e32 v56, v56, v59
	v_fmamk_f32 v59, v58, 0x37d75334, v62
	v_fmaak_f32 v59, v58, v59, 0x3d2aabf7
	v_fmaak_f32 v59, v58, v59, 0xbf000004
	v_fma_f32 v58, v58, v59, 1.0
	v_and_b32_e32 v59, 1, v55
	v_cmp_eq_u32_e32 vcc, 0, v59
	v_lshlrev_b32_e32 v55, 30, v55
	s_brev_b32 s11, 1
	v_cndmask_b32_e64 v56, -v56, v58, vcc
	v_bitop3_b32 v55, v55, v56, s11 bitop3:0x6c
	v_mul_f32_e32 v56, v38, v32
	v_mul_f32_e32 v58, 0x3fb8aa3b, v56
	v_fma_f32 v59, v56, s17, -v58
	v_rndne_f32_e32 v60, v58
	v_fmac_f32_e32 v59, 0x32a5705f, v56
	v_sub_f32_e32 v58, v58, v60
	v_add_f32_e32 v58, v58, v59
	v_exp_f32_e32 v58, v58
	v_cvt_i32_f32_e32 v59, v60
	v_cmp_ngt_f32_e32 vcc, s18, v56
	s_movk_i32 s16, 0x1f8
	v_mov_b32_e32 v63, 0x7fc00000
	v_ldexp_f32 v58, v58, v59
	v_cndmask_b32_e32 v58, 0, v58, vcc
	v_cmp_nlt_f32_e32 vcc, s19, v56
	v_cmp_class_f32_e64 s[4:5], v31, s16
	v_mov_b32_e32 v110, 0
	v_cndmask_b32_e32 v56, v64, v58, vcc
	v_mul_f32_e32 v58, v50, v50
	v_fmamk_f32 v59, v58, 0xb94c1982, v61
	v_fmaak_f32 v59, v58, v59, 0xbe2aaa9d
	v_mul_f32_e32 v59, v58, v59
	v_fmac_f32_e32 v50, v50, v59
	v_fmamk_f32 v59, v58, 0x37d75334, v62
	v_fmaak_f32 v59, v58, v59, 0x3d2aabf7
	v_fmaak_f32 v59, v58, v59, 0xbf000004
	v_fma_f32 v58, v58, v59, 1.0
	v_and_b32_e32 v59, 1, v48
	v_cmp_eq_u32_e32 vcc, 0, v59
	v_lshlrev_b32_e32 v48, 30, v48
	v_cndmask_b32_e64 v55, v63, v55, s[4:5]
	v_cndmask_b32_e64 v50, -v50, v58, vcc
	v_bitop3_b32 v48, v48, v50, s11 bitop3:0x6c
	v_mul_f32_e32 v50, v52, v52
	v_fmamk_f32 v58, v50, 0xb94c1982, v61
	v_fmaak_f32 v58, v50, v58, 0xbe2aaa9d
	v_mul_f32_e32 v58, v50, v58
	v_fmac_f32_e32 v52, v52, v58
	v_fmamk_f32 v58, v50, 0x37d75334, v62
	v_fmaak_f32 v58, v50, v58, 0x3d2aabf7
	v_fmaak_f32 v58, v50, v58, 0xbf000004
	v_fma_f32 v50, v50, v58, 1.0
	v_and_b32_e32 v58, 1, v51
	v_lshlrev_b32_e32 v51, 30, v51
	v_cmp_class_f32_e64 vcc, v46, s16
	v_cmp_eq_u32_e64 s[6:7], 0, v58
	v_and_b32_e32 v51, 0x80000000, v51
	v_xor_b32_e32 v46, v47, v46
	v_cndmask_b32_e64 v50, v50, v52, s[6:7]
	v_xor_b32_e32 v46, v46, v51
	v_xor_b32_e32 v46, v46, v50
	v_cndmask_b32_e32 v48, v63, v48, vcc
	v_cndmask_b32_e32 v46, v63, v46, vcc
	v_mul_f32_e32 v47, v56, v46
	v_fma_f32 v46, v56, v48, -1.0
	v_pk_mul_f32 v[50:51], v[32:33], v[46:47]
	v_lshl_add_u32 v115, v36, 2, s77
	v_add_f32_e32 v48, v50, v51
	v_mov_b32_e32 v50, v47
	v_mov_b32_e32 v51, v32
	v_pk_mul_f32 v[50:51], v[32:33], v[50:51] op_sel_hi:[0,1]
	v_mov_b32_e32 v32, v33
	v_mov_b32_e32 v47, v33
	v_pk_mul_f32 v[32:33], v[32:33], v[46:47] op_sel_hi:[0,1]
	v_add_f32_e32 v33, v51, v33
	v_div_scale_f32 v46, s[6:7], v33, v33, v48
	v_rcp_f32_e32 v47, v46
	v_sub_f32_e32 v32, v50, v32
	v_mov_b32_e32 v111, v110
	v_fma_f32 v51, -v46, v47, 1.0
	v_fmac_f32_e32 v47, v51, v47
	v_div_scale_f32 v51, vcc, v48, v33, v48
	v_mul_f32_e32 v52, v51, v47
	v_fma_f32 v56, -v46, v52, v51
	v_fmac_f32_e32 v52, v56, v47
	v_fma_f32 v46, -v46, v52, v51
	v_div_fmas_f32 v46, v46, v47, v52
	v_div_scale_f32 v47, s[6:7], v33, v33, v32
	v_div_fixup_f32 v46, v46, v33, v48
	v_rcp_f32_e32 v48, v47
	s_nop 0
	v_fma_f32 v50, -v47, v48, 1.0
	v_fmac_f32_e32 v48, v50, v48
	v_div_scale_f32 v50, vcc, v32, v33, v32
	v_mul_f32_e32 v51, v50, v48
	v_fma_f32 v52, -v47, v51, v50
	v_fmac_f32_e32 v51, v52, v48
	v_fma_f32 v47, -v47, v51, v50
	v_div_fmas_f32 v47, v47, v48, v51
	v_div_fixup_f32 v32, v47, v33, v32
	v_pk_mul_f32 v[50:51], v[18:19], v[46:47] op_sel_hi:[1,0]
	v_pk_mul_f32 v[18:19], v[18:19], v[32:33] op_sel_hi:[1,0]
	v_pk_fma_f32 v[50:51], v[14:15], v[32:33], v[50:51] op_sel_hi:[1,0,1]
	v_pk_fma_f32 v[14:15], v[14:15], v[46:47], v[18:19] op_sel_hi:[1,0,1] neg_lo:[0,0,1] neg_hi:[0,0,1]
	v_pk_mul_f32 v[18:19], v[20:21], v[46:47] op_sel_hi:[1,0]
	v_pk_mul_f32 v[20:21], v[20:21], v[32:33] op_sel_hi:[1,0]
	v_pk_fma_f32 v[18:19], v[16:17], v[32:33], v[18:19] op_sel_hi:[1,0,1]
	v_pk_fma_f32 v[16:17], v[16:17], v[46:47], v[20:21] op_sel_hi:[1,0,1] neg_lo:[0,0,1] neg_hi:[0,0,1]
	v_pk_mul_f32 v[20:21], v[10:11], v[46:47] op_sel_hi:[1,0]
	v_pk_mul_f32 v[10:11], v[10:11], v[32:33] op_sel_hi:[1,0]
	v_pk_fma_f32 v[20:21], v[6:7], v[32:33], v[20:21] op_sel_hi:[1,0,1]
	v_pk_fma_f32 v[6:7], v[6:7], v[46:47], v[10:11] op_sel_hi:[1,0,1] neg_lo:[0,0,1] neg_hi:[0,0,1]
	v_pk_mul_f32 v[10:11], v[46:47], v[12:13] op_sel_hi:[0,1]
	v_cvt_pk_bf16_f32 v68, v6, v7
	v_mul_f32_e32 v6, v45, v45
	v_fmamk_f32 v7, v6, 0xb94c1982, v61
	v_fmaak_f32 v7, v6, v7, 0xbe2aaa9d
	v_mul_f32_e32 v7, v6, v7
	v_fmac_f32_e32 v45, v45, v7
	v_fmamk_f32 v7, v6, 0x37d75334, v62
	v_fmaak_f32 v7, v6, v7, 0x3d2aabf7
	v_fmaak_f32 v7, v6, v7, 0xbf000004
	v_pk_mul_f32 v[12:13], v[32:33], v[12:13] op_sel_hi:[0,1]
	v_fma_f32 v6, v6, v7, 1.0
	v_and_b32_e32 v7, 1, v44
	v_pk_fma_f32 v[10:11], v[32:33], v[8:9], v[10:11] op_sel_hi:[0,1,1]
	v_pk_fma_f32 v[8:9], v[46:47], v[8:9], v[12:13] op_sel_hi:[0,1,1] neg_lo:[0,0,1] neg_hi:[0,0,1]
	v_cmp_eq_u32_e64 s[6:7], 0, v7
	v_lshlrev_b32_e32 v7, 30, v44
	v_cvt_pk_bf16_f32 v69, v8, v9
	v_and_b32_e32 v7, 0x80000000, v7
	v_xor_b32_e32 v8, v41, v40
	v_cndmask_b32_e64 v6, v6, v45, s[6:7]
	v_xor_b32_e32 v7, v8, v7
	v_cmp_class_f32_e64 vcc, v40, s16
	v_xor_b32_e32 v6, v7, v6
	v_cvt_pk_bf16_f32 v73, v10, v11
	v_cndmask_b32_e32 v11, v63, v6, vcc
	v_mul_f32_e32 v6, v38, v39
	v_mul_f32_e32 v7, 0x3fb8aa3b, v6
	v_fma_f32 v8, v6, s17, -v7
	v_rndne_f32_e32 v9, v7
	v_fmac_f32_e32 v8, 0x32a5705f, v6
	v_sub_f32_e32 v7, v7, v9
	v_add_f32_e32 v7, v7, v8
	v_exp_f32_e32 v7, v7
	v_cvt_i32_f32_e32 v8, v9
	v_cmp_ngt_f32_e64 s[6:7], s18, v6
	v_cvt_pk_bf16_f32 v66, v14, v15
	v_xor_b32_e32 v12, v49, v31
	v_ldexp_f32 v7, v7, v8
	v_cndmask_b32_e64 v7, 0, v7, s[6:7]
	v_cmp_nlt_f32_e64 s[6:7], s19, v6
	v_mul_f32_e32 v6, v43, v43
	v_mul_f32_e32 v8, v54, v54
	v_cndmask_b32_e64 v14, v64, v7, s[6:7]
	v_fmamk_f32 v7, v6, 0xb94c1982, v61
	v_fmaak_f32 v7, v6, v7, 0xbe2aaa9d
	v_mul_f32_e32 v7, v6, v7
	v_fmac_f32_e32 v43, v43, v7
	v_fmamk_f32 v7, v6, 0x37d75334, v62
	v_fmamk_f32 v10, v8, 0xb94c1982, v61
	v_fmaak_f32 v7, v6, v7, 0x3d2aabf7
	v_fmaak_f32 v10, v8, v10, 0xbe2aaa9d
	v_fmaak_f32 v7, v6, v7, 0xbf000004
	v_mul_f32_e32 v10, v8, v10
	v_fma_f32 v6, v6, v7, 1.0
	v_and_b32_e32 v7, 1, v42
	v_fmac_f32_e32 v54, v54, v10
	v_fmamk_f32 v10, v8, 0x37d75334, v62
	v_cmp_eq_u32_e64 s[6:7], 0, v7
	v_fmaak_f32 v10, v8, v10, 0x3d2aabf7
	v_lshlrev_b32_e32 v7, 30, v42
	v_cndmask_b32_e64 v6, -v43, v6, s[6:7]
	v_fmaak_f32 v10, v8, v10, 0xbf000004
	v_bitop3_b32 v6, v7, v6, s11 bitop3:0x6c
	v_fma_f32 v8, v8, v10, 1.0
	v_and_b32_e32 v10, 1, v53
	v_cndmask_b32_e32 v6, v63, v6, vcc
	v_cmp_eq_u32_e32 vcc, 0, v10
	v_lshlrev_b32_e32 v10, 30, v53
	v_and_b32_e32 v10, 0x80000000, v10
	v_cndmask_b32_e32 v8, v8, v54, vcc
	v_xor_b32_e32 v10, v12, v10
	v_xor_b32_e32 v8, v10, v8
	v_cndmask_b32_e64 v8, v63, v8, s[4:5]
	v_mul_f32_e32 v13, v57, v8
	v_fma_f32 v12, v57, v55, -1.0
	v_cvt_pk_bf16_f32 v67, v16, v17
	v_pk_mul_f32 v[16:17], v[34:35], v[12:13]
	v_and_b32_e32 v9, 15, v36
	v_add_f32_e32 v10, v16, v17
	v_mov_b32_e32 v16, v13
	v_mov_b32_e32 v17, v34
	v_mov_b32_e32 v8, v35
	v_mov_b32_e32 v13, v35
	v_pk_mul_f32 v[16:17], v[34:35], v[16:17] op_sel_hi:[0,1]
	v_pk_mul_f32 v[12:13], v[8:9], v[12:13] op_sel_hi:[0,1]
	v_add_f32_e32 v13, v17, v13
	v_div_scale_f32 v8, s[4:5], v13, v13, v10
	v_rcp_f32_e32 v15, v8
	v_cvt_pk_bf16_f32 v71, v18, v19
	v_cvt_pk_bf16_f32 v72, v20, v21
	s_lshl_b64 s[6:7], s[14:15], 2
	v_fma_f32 v17, -v8, v15, 1.0
	v_fmac_f32_e32 v15, v17, v15
	v_div_scale_f32 v17, vcc, v10, v13, v10
	v_mul_f32_e32 v18, v17, v15
	v_fma_f32 v19, -v8, v18, v17
	v_fmac_f32_e32 v18, v19, v15
	v_fma_f32 v8, -v8, v18, v17
	v_div_fmas_f32 v8, v8, v15, v18
	v_div_fixup_f32 v8, v8, v13, v10
	v_sub_f32_e32 v10, v16, v12
	v_div_scale_f32 v12, s[4:5], v13, v13, v10
	v_rcp_f32_e32 v15, v12
	v_mul_f32_e32 v104, v14, v6
	v_lshl_add_u64 v[6:7], v[2:3], 0, s[6:7]
	v_lshl_add_u64 v[2:3], v[24:25], 0, s[8:9]
	v_fma_f32 v16, -v12, v15, 1.0
	v_fmac_f32_e32 v15, v16, v15
	v_div_scale_f32 v16, vcc, v10, v13, v10
	v_mul_f32_e32 v17, v16, v15
	v_fma_f32 v18, -v12, v17, v16
	v_fmac_f32_e32 v17, v18, v15
	v_fma_f32 v12, -v12, v17, v16
	v_div_fmas_f32 v12, v12, v15, v17
	v_div_fixup_f32 v10, v12, v13, v10
	v_or_b32_e32 v12, 0x200, v30
	v_mov_b32_e32 v13, s13
	v_lshlrev_b64 v[16:17], 2, v[12:13]
	v_lshl_add_u64 v[20:21], v[26:27], 0, v[16:17]
	v_lshl_add_u64 v[28:29], v[28:29], 0, v[16:17]
	global_load_dwordx4 v[16:19], v[20:21], off
	global_load_dwordx4 v[24:27], v[28:29], off
	v_lshl_or_b32 v12, v9, 6, s12
	v_lshlrev_b64 v[12:13], 2, v[12:13]
	v_lshl_add_u64 v[4:5], v[4:5], 0, s[6:7]
	v_lshl_add_u64 v[4:5], v[4:5], 0, v[12:13]
	s_lshl_b32 s4, s10, 4
	v_readlane_b32 s6, v254, 54
	v_readlane_b32 s7, v254, 55
	s_ashr_i32 s5, s4, 31
	v_mul_f32_e32 v106, v14, v11
	v_lshlrev_b32_e32 v14, 4, v36
	v_cvt_pk_bf16_f32 v70, v50, v51
	v_mov_b32_e32 v105, v104
	v_mov_b32_e32 v107, v106
	v_add_u32_e32 v119, s77, v14
	s_waitcnt vmcnt(0) lgkmcnt(0)
	v_pk_mul_f32 v[30:31], v[24:25], v[8:9] op_sel_hi:[1,0]
	v_pk_mul_f32 v[24:25], v[24:25], v[10:11] op_sel_hi:[1,0]
	v_pk_fma_f32 v[30:31], v[16:17], v[10:11], v[30:31] op_sel_hi:[1,0,1]
	v_pk_fma_f32 v[32:33], v[16:17], v[8:9], v[24:25] op_sel_hi:[1,0,1] neg_lo:[0,0,1] neg_hi:[0,0,1]
	v_pk_mul_f32 v[16:17], v[26:27], v[8:9] op_sel_hi:[1,0]
	v_cvt_pk_bf16_f32 v74, v32, v33
	v_pk_fma_f32 v[34:35], v[18:19], v[10:11], v[16:17] op_sel_hi:[1,0,1]
	v_pk_mul_f32 v[16:17], v[26:27], v[10:11] op_sel_hi:[1,0]
	v_cvt_pk_bf16_f32 v78, v30, v31
	v_pk_fma_f32 v[38:39], v[18:19], v[8:9], v[16:17] op_sel_hi:[1,0,1] neg_lo:[0,0,1] neg_hi:[0,0,1]
	global_load_dwordx4 v[16:19], v[20:21], off offset:16
	global_load_dwordx4 v[24:27], v[28:29], off offset:16
	v_cvt_pk_bf16_f32 v75, v38, v39
	v_cvt_pk_bf16_f32 v79, v34, v35
	s_waitcnt vmcnt(0) lgkmcnt(0)
	v_pk_mul_f32 v[20:21], v[24:25], v[8:9] op_sel_hi:[1,0]
	v_pk_mul_f32 v[24:25], v[24:25], v[10:11] op_sel_hi:[1,0]
	v_pk_fma_f32 v[20:21], v[16:17], v[10:11], v[20:21] op_sel_hi:[1,0,1]
	v_pk_fma_f32 v[16:17], v[16:17], v[8:9], v[24:25] op_sel_hi:[1,0,1] neg_lo:[0,0,1] neg_hi:[0,0,1]
	v_pk_mul_f32 v[24:25], v[8:9], v[26:27] op_sel_hi:[0,1]
	v_pk_mul_f32 v[26:27], v[10:11], v[26:27] op_sel_hi:[0,1]
	v_cvt_pk_bf16_f32 v76, v16, v17
	v_lshl_add_u64 v[16:17], v[6:7], 0, v[12:13]
	v_and_b32_e32 v6, -4, v37
	v_pk_fma_f32 v[24:25], v[10:11], v[18:19], v[24:25] op_sel_hi:[0,1,1]
	v_pk_fma_f32 v[18:19], v[8:9], v[18:19], v[26:27] op_sel_hi:[0,1,1] neg_lo:[0,0,1] neg_hi:[0,0,1]
	v_ashrrev_i32_e32 v7, 31, v6
	v_cvt_pk_bf16_f32 v77, v18, v19
	v_lshlrev_b64 v[18:19], 2, v[6:7]
	v_cvt_pk_bf16_f32 v80, v20, v21
	v_lshl_add_u64 v[20:21], v[16:17], 0, v[18:19]
	v_cvt_pk_bf16_f32 v81, v24, v25
	v_lshl_add_u64 v[4:5], v[4:5], 0, v[18:19]
	global_load_dwordx4 v[16:19], v[20:21], off
	global_load_dwordx4 v[24:27], v[4:5], off
	v_and_b32_e32 v8, 1, v36
	v_lshlrev_b32_e32 v15, 5, v6
	v_mov_b32_e32 v6, 0x60
	v_lshl_add_u32 v13, v9, 1, s77
	v_add_u32_e32 v117, v13, v15
	s_waitcnt vmcnt(0) lgkmcnt(0)
	v_xor_b32_e32 v7, 0x80000000, v24
	v_cvt_pk_bf16_f32 v82, v16, v7
	v_xor_b32_e32 v7, 0x80000000, v25
	v_cvt_pk_bf16_f32 v83, v17, v7
	v_xor_b32_e32 v7, 0x80000000, v26
	v_cvt_pk_bf16_f32 v84, v18, v7
	v_xor_b32_e32 v7, 0x80000000, v27
	v_cvt_pk_bf16_f32 v85, v19, v7
	global_load_dwordx4 v[16:19], v[20:21], off offset:64
	global_load_dwordx4 v[24:27], v[4:5], off offset:64
	s_waitcnt vmcnt(0) lgkmcnt(0)
	v_xor_b32_e32 v7, 0x80000000, v24
	v_cvt_pk_bf16_f32 v86, v16, v7
	v_xor_b32_e32 v7, 0x80000000, v25
	v_cvt_pk_bf16_f32 v87, v17, v7
	v_xor_b32_e32 v7, 0x80000000, v26
	v_cvt_pk_bf16_f32 v88, v18, v7
	v_xor_b32_e32 v7, 0x80000000, v27
	v_cvt_pk_bf16_f32 v89, v19, v7
	global_load_dwordx4 v[16:19], v[20:21], off offset:128
	global_load_dwordx4 v[24:27], v[4:5], off offset:128
	s_waitcnt vmcnt(0) lgkmcnt(0)
	v_xor_b32_e32 v7, 0x80000000, v24
	v_cvt_pk_bf16_f32 v90, v16, v7
	v_xor_b32_e32 v7, 0x80000000, v25
	v_cvt_pk_bf16_f32 v91, v17, v7
	v_xor_b32_e32 v7, 0x80000000, v26
	v_cvt_pk_bf16_f32 v92, v18, v7
	v_xor_b32_e32 v7, 0x80000000, v27
	v_cvt_pk_bf16_f32 v93, v19, v7
	global_load_dwordx4 v[16:19], v[20:21], off offset:192
	global_load_dwordx4 v[24:27], v[4:5], off offset:192
	v_lshlrev_b32_e32 v7, 1, v22
	s_waitcnt vmcnt(0) lgkmcnt(0)
	v_xor_b32_e32 v4, 0x80000000, v24
	v_cvt_pk_bf16_f32 v94, v16, v4
	v_xor_b32_e32 v4, 0x80000000, v25
	v_cvt_pk_bf16_f32 v95, v17, v4
	v_xor_b32_e32 v4, 0x80000000, v26
	v_cvt_pk_bf16_f32 v96, v18, v4
	v_xor_b32_e32 v4, 0x80000000, v27
	v_cvt_pk_bf16_f32 v97, v19, v4
	v_or_b32_e32 v4, s4, v9
	v_ashrrev_i32_e32 v5, 31, v4
	v_lshl_add_u64 v[2:3], v[4:5], 2, v[2:3]
	global_load_dword v114, v[2:3], off
	v_lshl_add_u64 v[2:3], v[154:155], 0, s[6:7]
	s_lshl_b64 s[4:5], s[4:5], 1
	v_mul_u32_u24_e32 v4, 0xa00, v0
	v_lshl_add_u64 v[2:3], v[2:3], 0, s[4:5]
	v_lshlrev_b32_e32 v4, 1, v4
	v_mov_b32_e32 v5, v1
	v_lshl_add_u64 v[2:3], v[2:3], 0, v[4:5]
	v_lshl_add_u64 v[108:109], v[22:23], 1, v[2:3]
	global_load_dwordx4 v[2:5], v[108:109], off offset:3840
	v_lshlrev_b32_e32 v0, 5, v0
	v_add3_u32 v0, s77, v0, v7
	v_and_b32_e32 v7, -16, v36
	v_add_u32_e32 v12, s77, v7
	v_ashrrev_i32_e32 v7, 1, v36
	v_mad_i64_i32 v[10:11], s[6:7], v7, s61, 0
	v_readlane_b32 s6, v254, 56
	v_readlane_b32 s7, v254, 57
	v_lshl_or_b32 v10, v8, 4, v10
	v_mul_u32_u24_e32 v16, 0x210, v9
	v_lshl_or_b32 v17, v37, 5, v6
	v_lshl_add_u64 v[6:7], v[102:103], 0, s[6:7]
	v_lshl_add_u64 v[8:9], v[10:11], 0, s[4:5]
	v_lshl_add_u64 v[112:113], v[6:7], 0, v[8:9]
	s_mov_b32 s4, 0x14000
	v_add_u32_e32 v116, v12, v16
	v_add_u32_e32 v118, v13, v17
	s_waitcnt vmcnt(0)
	s_setprio 1

.LBB0_432:
	s_setprio 0
	v_add_co_u32_e32 v2, vcc, 0x1eb89000, v102
	s_getreg_b32 s4, hwreg(HW_REG_XCC_ID, 0, 4)
	s_nop 0
	v_addc_co_u32_e32 v3, vcc, 0, v103, vcc
	v_add_co_u32_e32 v238, vcc, 0x1eb8a000, v102
	s_nop 1
	v_addc_co_u32_e32 v239, vcc, 0, v103, vcc
	global_load_dword v222, v[2:3], off offset:1024 sc1
	global_load_dword v223, v[2:3], off offset:1280 sc1
	global_load_dword v224, v[2:3], off offset:1536 sc1
	global_load_dword v225, v[2:3], off offset:1792 sc1
	global_load_dword v226, v[2:3], off offset:2048 sc1
	global_load_dword v227, v[2:3], off offset:2304 sc1
	global_load_dword v228, v[2:3], off offset:2560 sc1
	global_load_dword v229, v[2:3], off offset:2816 sc1
	global_load_dword v230, v[2:3], off offset:3072 sc1
	global_load_dword v231, v[2:3], off offset:3328 sc1
	global_load_dword v232, v[2:3], off offset:3584 sc1
	global_load_dword v233, v[2:3], off offset:3840 sc1
	global_load_dword v234, v[238:239], off sc1
	global_load_dword v235, v[238:239], off offset:256 sc1
	global_load_dword v236, v[238:239], off offset:512 sc1
	global_load_dword v237, v[238:239], off offset:768 sc1
	s_waitcnt vmcnt(0)
	v_mov_b32_e32 v0, v222
	v_mov_b32_e32 v4, v223
	v_mov_b32_e32 v6, v224
	s_and_b32 s7, s4, 15
	s_cmp_lg_u32 s7, 0
	s_cselect_b64 s[4:5], -1, 0
	s_mov_b32 s6, 0
	s_mov_b32 s37, 0
	s_waitcnt vmcnt(0) lgkmcnt(0)
	v_cmp_ne_u32_e32 vcc, 0, v0
	s_and_b64 s[4:5], vcc, s[4:5]
	s_cmp_gt_u32 s7, 1
	v_cndmask_b32_e64 v0, 0, 1, s[4:5]
	v_cmp_ne_u32_e64 s[4:5], 0, v4
	s_cselect_b64 s[8:9], -1, 0
	s_nop 0
	v_cndmask_b32_e64 v4, 0, 1, s[4:5]
	s_and_b64 s[4:5], s[4:5], s[8:9]
	v_addc_co_u32_e32 v4, vcc, 0, v4, vcc
	s_cmp_gt_u32 s7, 2
	v_cndmask_b32_e64 v5, 0, 1, s[4:5]
	v_cmp_ne_u32_e32 vcc, 0, v6
	s_cselect_b64 s[4:5], -1, 0
	s_nop 0
	v_cndmask_b32_e64 v6, 0, 1, vcc
	s_and_b64 vcc, vcc, s[4:5]
	v_addc_co_u32_e32 v0, vcc, v0, v5, vcc
	v_mov_b32_e32 v5, v225
	s_cmp_gt_u32 s7, 3
	s_cselect_b64 s[8:9], -1, 0
	s_waitcnt vmcnt(0) lgkmcnt(0)
	v_cmp_ne_u32_e32 vcc, 0, v5
	s_nop 1
	v_addc_co_u32_e64 v4, s[4:5], v4, v6, vcc
	v_mov_b32_e32 v6, v226
	s_and_b64 s[4:5], vcc, s[8:9]
	s_cmp_gt_u32 s7, 4
	v_cndmask_b32_e64 v5, 0, 1, s[4:5]
	s_cselect_b64 s[4:5], -1, 0
	s_waitcnt vmcnt(0) lgkmcnt(0)
	v_cmp_ne_u32_e32 vcc, 0, v6
	s_nop 1
	v_cndmask_b32_e64 v6, 0, 1, vcc
	s_and_b64 vcc, vcc, s[4:5]
	v_addc_co_u32_e32 v0, vcc, v0, v5, vcc
	v_mov_b32_e32 v5, v227
	s_cmp_gt_u32 s7, 5
	s_cselect_b64 s[8:9], -1, 0
	s_waitcnt vmcnt(0) lgkmcnt(0)
	v_cmp_ne_u32_e32 vcc, 0, v5
	s_nop 1
	v_addc_co_u32_e64 v4, s[4:5], v4, v6, vcc
	v_mov_b32_e32 v6, v228
	s_and_b64 s[4:5], vcc, s[8:9]
	s_cmp_gt_u32 s7, 6
	v_cndmask_b32_e64 v5, 0, 1, s[4:5]
	s_cselect_b64 s[4:5], -1, 0
	s_waitcnt vmcnt(0) lgkmcnt(0)
	v_cmp_ne_u32_e32 vcc, 0, v6
	s_nop 1
	v_cndmask_b32_e64 v6, 0, 1, vcc
	s_and_b64 vcc, vcc, s[4:5]
	v_addc_co_u32_e32 v0, vcc, v0, v5, vcc
	v_mov_b32_e32 v5, v229
	s_cmp_gt_u32 s7, 7
	s_cselect_b64 s[8:9], -1, 0
	s_waitcnt vmcnt(0) lgkmcnt(0)
	v_cmp_ne_u32_e32 vcc, 0, v5
	s_nop 1
	v_addc_co_u32_e64 v4, s[4:5], v4, v6, vcc
	v_mov_b32_e32 v6, v230
	s_and_b64 s[4:5], vcc, s[8:9]
	s_cmp_gt_u32 s7, 8
	v_cndmask_b32_e64 v5, 0, 1, s[4:5]
	s_cselect_b64 s[4:5], -1, 0
	s_waitcnt vmcnt(0) lgkmcnt(0)
	v_cmp_ne_u32_e32 vcc, 0, v6
	s_nop 1
	v_cndmask_b32_e64 v6, 0, 1, vcc
	s_and_b64 vcc, vcc, s[4:5]
	v_addc_co_u32_e32 v0, vcc, v0, v5, vcc
	v_mov_b32_e32 v5, v231
	s_cmp_gt_u32 s7, 9
	s_cselect_b64 s[8:9], -1, 0
	s_waitcnt vmcnt(0) lgkmcnt(0)
	v_cmp_ne_u32_e32 vcc, 0, v5
	s_nop 1
	v_addc_co_u32_e64 v4, s[4:5], v4, v6, vcc
	v_mov_b32_e32 v6, v232
	s_and_b64 s[4:5], vcc, s[8:9]
	v_mov_b32_e32 v2, v233
	s_cmp_gt_u32 s7, 10
	v_cndmask_b32_e64 v5, 0, 1, s[4:5]
	s_cselect_b64 s[4:5], -1, 0
	s_waitcnt vmcnt(0) lgkmcnt(0)
	v_cmp_ne_u32_e32 vcc, 0, v6
	s_nop 1
	v_cndmask_b32_e64 v6, 0, 1, vcc
	s_and_b64 vcc, vcc, s[4:5]
	v_addc_co_u32_e32 v0, vcc, v0, v5, vcc
	v_cmp_ne_u32_e32 vcc, 0, v2
	s_cmp_gt_u32 s7, 11
	s_cselect_b64 s[8:9], -1, 0
	v_addc_co_u32_e64 v4, s[4:5], v4, v6, vcc
	s_and_b64 s[4:5], vcc, s[8:9]
	s_nop 0
	v_cndmask_b32_e64 v5, 0, 1, s[4:5]
	s_mov_b32 s4, 0x1eb8a000
	v_add_co_u32_e32 v2, vcc, s4, v102
	s_cmp_gt_u32 s7, 12
	s_nop 0
	v_addc_co_u32_e32 v3, vcc, 0, v103, vcc
	v_mov_b32_e32 v6, v234
	s_cselect_b64 s[4:5], -1, 0
	s_waitcnt vmcnt(0) lgkmcnt(0)
	v_cmp_ne_u32_e32 vcc, 0, v6
	s_nop 1
	v_cndmask_b32_e64 v6, 0, 1, vcc
	s_and_b64 vcc, vcc, s[4:5]
	v_addc_co_u32_e32 v0, vcc, v0, v5, vcc
	v_mov_b32_e32 v5, v235
	s_cmp_gt_u32 s7, 13
	s_cselect_b64 s[8:9], -1, 0
	s_waitcnt vmcnt(0) lgkmcnt(0)
	v_cmp_ne_u32_e32 vcc, 0, v5
	s_nop 1
	v_addc_co_u32_e64 v4, s[4:5], v4, v6, vcc
	v_mov_b32_e32 v6, v236
	s_and_b64 s[4:5], vcc, s[8:9]
	v_mov_b32_e32 v2, v237
	s_cmp_eq_u32 s7, 15
	v_cndmask_b32_e64 v5, 0, 1, s[4:5]
	s_cselect_b64 s[4:5], -1, 0
	s_waitcnt vmcnt(0) lgkmcnt(0)
	v_cmp_ne_u32_e32 vcc, 0, v6
	s_nop 1
	v_cndmask_b32_e64 v6, 0, 1, vcc
	s_and_b64 vcc, vcc, s[4:5]
	v_addc_co_u32_e32 v0, vcc, v0, v5, vcc
	v_cmp_ne_u32_e32 vcc, 0, v2
	v_readfirstlane_b32 s80, v0
	s_nop 0
	v_addc_co_u32_e32 v2, vcc, v4, v6, vcc
	s_nop 0
	v_readfirstlane_b32 s4, v2
	s_max_u32 s36, s4, 1
	v_cvt_f32_u32_e32 v0, s36
	s_cmp_gt_u32 s80, 15
	v_rcp_iflag_f32_e32 v0, v0
	s_cbranch_scc1 .LBB0_434
	v_mul_f32_e32 v2, 0x4f7ffffe, v0
	v_cvt_u32_f32_e32 v2, v2
	s_sub_i32 s5, 0, s36
	s_sub_i32 s4, s36, s80
	s_add_i32 s4, s4, 15
	v_readfirstlane_b32 s7, v2
	s_mul_i32 s5, s5, s7
	s_mul_hi_u32 s5, s7, s5
	s_add_i32 s7, s7, s5
	s_mul_hi_u32 s5, s4, s7
	s_mul_i32 s7, s5, s36
	s_sub_i32 s4, s4, s7
	s_add_i32 s7, s5, 1
	s_sub_i32 s8, s4, s36
	s_cmp_ge_u32 s4, s36
	s_cselect_b32 s5, s7, s5
	s_cselect_b32 s4, s8, s4
	s_add_i32 s7, s5, 1
	s_cmp_ge_u32 s4, s36
	s_cselect_b32 s37, s7, s5
